# ssm pass2: ud via identity MFMA instead of 4 ushort loads; uh wait moved to loop bottom as vmcnt(4)
# speedup vs baseline: 1.0016x; 1.0016x over previous
; #define LAS __attribute__((address_space(3)))
; __device__ __forceinline__ void ssm_pass2(LAS unsigned char* lds, const bf16_t* US, const float* SST, bf16_t* YB, const float* ABAR, const bf16_t* BBH, const bf16_t* BBL, const bf16_t* CMH, const bf16_t* CML, const float* dco, int gw, int NGW, int lane, int wave) {
;     LAS float* tile = (LAS float*)(lds + wave * (16 * TSTR * 4));
;     const int fr = lane & 15, fq = lane >> 4;
;     for (int idx = gw; idx < NB * NG * 8; idx += NGW) {
;         const int c = idx & 7, bg = idx >> 3, b = bg >> 5, g = bg & 31;
;         SsmOps S; ssm_ops_load(S, ABAR, BBH, BBL, g, lane);
;         bf16x8 ch[4];
; #pragma unroll
;         for (int ks = 0; ks < 4; ++ks) { const size_t o = (size_t)(g * 16 + fr) * 128 + ks * 32 + fq * 8; ch[ks] = *(const bf16x8*)(CMH + o); }
;         const float dh = dco[g * 16 + fr];
;         float pr = S.ar, pi = S.ai;
; #pragma unroll
;         for (int s = 0; s < 8; ++s) { const float nr = pr * pr - pi * pi, ni = 2.f * pr * pi; pr = nr; pi = ni; }
;         float xr = 0.f, xi = 0.f;
;         { float sr[7], sm[7];
; #pragma unroll
;           for (int cc = 0; cc < 7; ++cc) { const float* si = SST + ((size_t)bg * 8 + (cc < c ? cc : 0)) * 128; sr[cc] = si[lane]; sm[cc] = si[64 + lane]; }
; #pragma unroll
;           for (int cc = 0; cc < 7; ++cc) if (cc < c) { const float nr = pr * xr - pi * xi + sr[cc], ni = pr * xi + pi * xr + sm[cc]; xr = nr; xi = ni; } }
;         const int tokc = b * SEQ + c * 256;
;         bf16x8 uh; ssm_u_load(uh, US, tokc, g, lane);
.LBB0_544:
	s_cmp_lt_i32 s30, 6
	s_cselect_b64 s[8:9], -1, 0
	s_add_u32 s0, s28, 0x10800000
	s_addc_u32 s1, s29, 0
	s_and_b64 s[48:49], s[8:9], s[4:5]
	s_andn2_b64 vcc, exec, s[48:49]
	s_cbranch_vccnz .LBB0_552
	s_cmpk_gt_i32 s92, 0xfff
	s_cbranch_scc1 .LBB0_552
	v_and_b32_e32 v160, 15, v196
	v_lshrrev_b32_e32 v161, 4, v196
	v_lshrrev_b32_e32 v162, 3, v160
	v_and_b32_e32 v163, 1, v160
	v_lshlrev_b32_e32 v163, 4, v163
	v_mov_b32_e32 v164, 0x3f80
	v_lshlrev_b32_e32 v164, v163, v164
	v_cmp_eq_u32_e32 vcc, v161, v162
	v_bfe_u32 v165, v160, 1, 2
	s_nop 1
	v_cndmask_b32_e32 v164, 0, v164, vcc
	v_cmp_eq_u32_e32 vcc, 0, v165
	s_nop 1
	v_cndmask_b32_e32 v152, 0, v164, vcc
	v_cmp_eq_u32_e32 vcc, 1, v165
	s_nop 1
	v_cndmask_b32_e32 v153, 0, v164, vcc
	v_cmp_eq_u32_e32 vcc, 2, v165
	s_nop 1
	v_cndmask_b32_e32 v154, 0, v164, vcc
	v_cmp_eq_u32_e32 vcc, 3, v165
	s_nop 1
	v_cndmask_b32_e32 v155, 0, v164, vcc
	s_add_u32 s50, s28, 0x100000
	s_addc_u32 s51, s29, 0
	s_add_u32 s52, s28, 0x110000
	s_addc_u32 s53, s29, 0
	v_readlane_b32 s60, v249, 18
	v_lshrrev_b32_e32 v0, 1, v197
	s_add_u32 s54, s28, 0x160000
	v_and_b32_e32 v114, 15, v197
	s_mul_i32 s3, s60, 0x2100
	v_and_b32_e32 v0, 8, v0
	v_lshlrev_b32_e32 v2, 4, v197
	s_movk_i32 s8, 0xf0
	s_addc_u32 s55, s29, 0
	s_add_i32 s3, s3, 0
	s_waitcnt lgkmcnt(0)
	v_lshrrev_b32_e32 v1, 4, v196
	v_and_or_b32 v115, v2, s8, v0
	v_lshlrev_b32_e32 v2, 7, v114
	v_lshlrev_b32_e32 v80, 2, v196
	v_lshl_or_b32 v116, v1, 3, v2
	v_mov_b32_e32 v2, s3
	v_add_u32_e32 v119, s3, v80
	s_bfe_u32 s3, s97, 0x30006
	s_movk_i32 s8, 0x210
	s_cmp_gt_u32 s3, 1
	v_mad_u32_u24 v5, v114, s8, v2
	s_cselect_b64 s[8:9], -1, 0
	s_and_b64 s[10:11], s[8:9], exec
	s_cselect_b32 s56, 0x80, 0
	s_cmp_gt_u32 s3, 2
	s_cselect_b64 s[10:11], -1, 0
	s_and_b64 s[12:13], s[10:11], exec
	s_cselect_b32 s58, 0x100, 0
	s_cmp_gt_u32 s3, 3
	s_cselect_b64 s[12:13], -1, 0
	s_and_b64 s[14:15], s[12:13], exec
	s_cselect_b32 s59, 0x180, 0
	s_cmp_gt_u32 s3, 4
	s_cselect_b64 s[14:15], -1, 0
	s_and_b64 s[16:17], s[14:15], exec
	s_cselect_b32 s61, 0x200, 0
	s_cmp_gt_u32 s3, 5
	s_cselect_b64 s[16:17], -1, 0
	s_and_b64 s[18:19], s[16:17], exec
	s_cselect_b32 s63, 0x280, 0
	s_cmp_eq_u32 s3, 7
	s_cselect_b64 s[18:19], -1, 0
	v_mov_b32_e32 v81, 0
	v_and_b32_e32 v2, 48, v197
	s_and_b64 s[20:21], s[18:19], exec
	v_add_u32_e32 v117, v5, v2
	v_lshlrev_b32_e32 v2, 1, v0
	v_mov_b32_e32 v3, v81
	s_cselect_b32 s20, 0x300, 0
	s_cmp_lg_u32 s3, 0
	v_lshlrev_b32_e32 v4, 1, v196
	v_lshl_add_u64 v[84:85], s[46:47], 0, v[2:3]
	v_lshlrev_b32_e32 v118, 2, v1
	v_lshlrev_b32_e32 v2, 1, v114
	v_lshlrev_b32_e32 v1, 5, v1
	s_cselect_b64 s[34:35], -1, 0
	s_lshl_b32 s3, s3, 8
	s_lshl_b32 s21, s2, 6
	s_lshl_b32 s60, s60, 3
	s_mov_b32 s57, 0
	v_cmp_gt_u32_e64 s[4:5], 32, v196
	v_lshl_add_u64 v[82:83], s[6:7], 0, v[80:81]
	v_cmp_lt_u32_e64 s[6:7], 31, v196
	v_lshl_add_u64 v[86:87], s[46:47], 0, v[2:3]
	v_lshl_add_u64 v[88:89], s[0:1], 0, v[2:3]
	v_or_b32_e32 v120, s3, v118
	s_add_i32 s68, s21, s60
	s_lshl_b32 s69, s22, 6
	v_or3_b32 v121, s3, v114, 16
	v_lshlrev_b32_e32 v122, 2, v4
	s_lshl_b32 s56, s56, 2
	s_lshl_b32 s58, s58, 2
	s_lshl_b32 s60, s59, 2
	s_lshl_b32 s62, s61, 2
	s_lshl_b32 s64, s63, 2
	s_lshl_b32 s66, s20, 2
	v_lshlrev_b32_e32 v80, 1, v0
	v_add_u32_e32 v123, v5, v1
	s_mov_b32 s70, s92

; #define LAS __attribute__((address_space(3)))
; __device__ __forceinline__ void ssm_bu_tile(const SsmOps& S, bf16x8 uh, LAS float* tile, int lane) {
;     const int fr = lane & 15, fq = lane >> 4;
;     if (fq >= 2) uh = (bf16x8){0, 0, 0, 0, 0, 0, 0, 0};
; #pragma unroll
;     for (int nb = 0; nb < 8; ++nb) { f32x4 acc = {0.f, 0.f, 0.f, 0.f};
;         acc = __builtin_amdgcn_mfma_f32_16x16x32_bf16(S.bh[nb], uh, acc, 0, 0, 0);
;         *(LAS f32x4*)(tile + fr * TSTR + 16 * nb + 4 * fq) = acc; }
; __device__ __forceinline__ void ssm_pass2(LAS unsigned char* lds, const bf16_t* US, const float* SST, bf16_t* YB, const float* ABAR, const bf16_t* BBH, const bf16_t* BBL, const bf16_t* CMH, const bf16_t* CML, const float* dco, int gw, int NGW, int lane, int wave) {
;     ...
;           for (int cc = 0; cc < 7; ++cc) { const float* si = SST + ((size_t)bg * 8 + (cc < c ? cc : 0)) * 128; sr[cc] = si[lane]; sm[cc] = si[64 + lane]; }
; #pragma unroll
;           for (int cc = 0; cc < 7; ++cc) if (cc < c) { const float nr = pr * xr - pi * xi + sr[cc], ni = pr * xi + pi * xr + sm[cc]; xr = nr; xi = ni; } }
;         const int tokc = b * SEQ + c * 256;
;         bf16x8 uh; ssm_u_load(uh, US, tokc, g, lane);
;         for (int grp = 0; grp < 16; ++grp) { const int tok = tokc + grp * 16;
;             ssm_bu_tile(S, uh, tile, lane);
;             if (grp < 15) ssm_u_load(uh, US, tok + 16, g, lane);
;             float ud[4];
; #pragma unroll
;             for (int i = 0; i < 4; ++i) ud[i] = bf_lo((unsigned)US[(size_t)(tok + 4 * fq + i) * SSMW + g * 16 + fr]);
.LBB0_549:
	s_and_b32 s21, s68, 0xfffff800
	v_or_b32_e32 v125, s21, v120
	v_or_b32_e32 v126, s21, v121
	s_lshl_b32 s21, s70, 3
	v_mul_f32_e32 v48, v66, v52
	s_and_b32 s21, s21, 0xfffff800
	v_fma_f32 v48, v65, v53, -v48
	s_or_b32 s59, s21, s3
	v_add_f32_e32 v68, v50, v48
	v_or_b32_e32 v48, s59, v114
	v_ashrrev_i32_e32 v49, 31, v48
	v_lshlrev_b64 v[48:49], 10, v[48:49]
	v_lshl_add_u64 v[48:49], s[46:47], 0, v[48:49]
	s_lshl_b32 s20, s20, 1
	s_mov_b32 s21, s57
	v_lshl_add_u64 v[48:49], v[48:49], 0, s[20:21]
	v_lshl_add_u64 v[48:49], v[48:49], 0, v[80:81]
	global_load_dwordx4 v[48:51], v[48:49], off
	v_mul_f32_e32 v67, v66, v53
	v_fmac_f32_e32 v67, v65, v52
	v_add_f32_e32 v64, v64, v67
	v_cndmask_b32_e64 v52, v52, v64, s[8:9]
	v_cndmask_b32_e64 v53, v53, v68, s[8:9]
	v_mul_f32_e32 v64, v66, v53
	v_mul_f32_e32 v67, v66, v52
	v_fmac_f32_e32 v64, v65, v52
	v_fma_f32 v67, v65, v53, -v67
	v_add_f32_e32 v62, v62, v67
	v_add_f32_e32 v63, v63, v64
	v_cndmask_b32_e64 v52, v52, v63, s[10:11]
	v_cndmask_b32_e64 v53, v53, v62, s[10:11]
	v_mul_f32_e32 v62, v66, v53
	v_mul_f32_e32 v63, v66, v52
	v_fmac_f32_e32 v62, v65, v52
	v_fma_f32 v63, v65, v53, -v63
	v_add_f32_e32 v60, v60, v63
	v_add_f32_e32 v61, v61, v62
	v_cndmask_b32_e64 v52, v52, v61, s[12:13]
	v_cndmask_b32_e64 v53, v53, v60, s[12:13]
	v_mul_f32_e32 v60, v66, v53
	v_mul_f32_e32 v61, v66, v52
	v_fmac_f32_e32 v60, v65, v52
	v_fma_f32 v61, v65, v53, -v61
	v_add_f32_e32 v56, v56, v61
	v_add_f32_e32 v57, v57, v60
	v_cndmask_b32_e64 v52, v52, v57, s[14:15]
	v_cndmask_b32_e64 v53, v53, v56, s[14:15]
	v_mul_f32_e32 v56, v66, v53
	v_mul_f32_e32 v57, v66, v52
	v_fmac_f32_e32 v56, v65, v52
	v_fma_f32 v57, v65, v53, -v57
	v_add_f32_e32 v57, v58, v57
	v_add_f32_e32 v56, v59, v56
	v_cndmask_b32_e64 v52, v52, v56, s[16:17]
	v_cndmask_b32_e64 v53, v53, v57, s[16:17]
	v_mul_f32_e32 v56, v66, v53
	v_mul_f32_e32 v57, v66, v52
	v_fmac_f32_e32 v56, v65, v52
	v_fma_f32 v57, v65, v53, -v57
	v_add_f32_e32 v54, v54, v57
	v_add_f32_e32 v55, v55, v56
	v_pk_mov_b32 v[94:95], v[90:91], v[90:91] op_sel:[1,0]
	v_cndmask_b32_e64 v76, v52, v55, s[18:19]
	v_cndmask_b32_e64 v100, v53, v54, s[18:19]
	v_cndmask_b32_e64 v19, 0, v19, s[4:5]
	v_cndmask_b32_e64 v18, 0, v18, s[4:5]
	v_cndmask_b32_e64 v17, 0, v17, s[4:5]
	v_cndmask_b32_e64 v16, 0, v16, s[4:5]
	v_cndmask_b32_e64 v23, 0, v23, s[4:5]
	v_cndmask_b32_e64 v22, 0, v22, s[4:5]
	v_cndmask_b32_e64 v21, 0, v21, s[4:5]
	v_cndmask_b32_e64 v20, 0, v20, s[4:5]
	v_cndmask_b32_e64 v27, 0, v27, s[4:5]
	v_cndmask_b32_e64 v26, 0, v26, s[4:5]
	v_cndmask_b32_e64 v25, 0, v25, s[4:5]
	v_cndmask_b32_e64 v24, 0, v24, s[4:5]
	v_cndmask_b32_e64 v31, 0, v31, s[4:5]
	v_cndmask_b32_e64 v30, 0, v30, s[4:5]
	v_cndmask_b32_e64 v29, 0, v29, s[4:5]
	v_cndmask_b32_e64 v28, 0, v28, s[4:5]
	v_cndmask_b32_e64 v35, 0, v35, s[4:5]
	v_cndmask_b32_e64 v34, 0, v34, s[4:5]
	v_cndmask_b32_e64 v33, 0, v33, s[4:5]
	v_cndmask_b32_e64 v32, 0, v32, s[4:5]
	v_cndmask_b32_e64 v39, 0, v39, s[4:5]
	v_cndmask_b32_e64 v38, 0, v38, s[4:5]
	v_cndmask_b32_e64 v37, 0, v37, s[4:5]
	v_cndmask_b32_e64 v36, 0, v36, s[4:5]
	v_cndmask_b32_e64 v43, 0, v43, s[4:5]
	v_cndmask_b32_e64 v42, 0, v42, s[4:5]
	v_cndmask_b32_e64 v41, 0, v41, s[4:5]
	v_cndmask_b32_e64 v40, 0, v40, s[4:5]
	v_cndmask_b32_e64 v47, 0, v47, s[4:5]
	v_cndmask_b32_e64 v46, 0, v46, s[4:5]
	v_cndmask_b32_e64 v45, 0, v45, s[4:5]
	v_cndmask_b32_e64 v44, 0, v44, s[4:5]
	v_lshl_add_u64 v[98:99], v[84:85], 0, s[20:21]
	v_lshl_add_u64 v[96:97], v[86:87], 0, s[20:21]
	v_lshl_add_u64 v[92:93], v[88:89], 0, s[20:21]
	s_mov_b32 s20, 0
	s_waitcnt vmcnt(0)
.LBB0_550:
	v_cndmask_b32_e64 v105, v51, 0, s[6:7]
	v_cndmask_b32_e64 v104, v50, 0, s[6:7]
	v_cndmask_b32_e64 v103, v49, 0, s[6:7]
	v_cndmask_b32_e64 v102, v48, 0, s[6:7]
	v_add_u32_e32 v108, s20, v125
	v_add_u32_e32 v106, s20, v126
	v_mfma_f32_16x16x32_bf16 v[48:51], v[16:19], v[102:105], 0
	v_add_u32_e32 v112, 1, v108
	v_add_u32_e32 v142, 2, v108
	v_pk_mul_f32 v[110:111], v[94:95], v[76:77] op_sel_hi:[1,0]
	v_mfma_f32_16x16x32_bf16 v[52:55], v[20:23], v[102:105], 0
	v_ashrrev_i32_e32 v107, 31, v106
	v_ashrrev_i32_e32 v109, 31, v108
	v_add_u32_e32 v144, 3, v108
	v_mfma_f32_16x16x32_bf16 v[56:59], v[24:27], v[102:105], 0
	v_ashrrev_i32_e32 v113, 31, v112
	v_ashrrev_i32_e32 v143, 31, v142
	v_ashrrev_i32_e32 v145, 31, v144
	v_mfma_f32_16x16x32_bf16 v[60:63], v[28:31], v[102:105], 0
	v_lshlrev_b64 v[112:113], 10, v[112:113]
	v_add_u32_e32 v127, 32, v119
	v_add_u32_e32 v128, 48, v119
	v_mfma_f32_16x16x32_bf16 v[64:67], v[32:35], v[102:105], 0
	v_add_u32_e32 v129, 64, v119
	v_add_u32_e32 v130, 0x50, v119
	v_add_u32_e32 v131, 0x60, v119
	v_mfma_f32_16x16x32_bf16 v[68:71], v[36:39], v[102:105], 0
	v_add_u32_e32 v132, 0x70, v119
	v_add_u32_e32 v133, 0x80, v119
	v_add_u32_e32 v134, 0x90, v119
	v_mfma_f32_16x16x32_bf16 v[72:75], v[40:43], v[102:105], 0
	v_add_u32_e32 v135, 0xa0, v119
	v_add_u32_e32 v136, 0xb0, v119
	v_add_u32_e32 v137, 0xc0, v119
	v_mfma_f32_16x16x32_bf16 v[76:79], v[44:47], v[102:105], 0
	v_mfma_f32_16x16x32_bf16 v[156:159], v[102:105], v[152:155], 0
	v_fma_f32 v102, v90, v100, -v110
	v_fma_f32 v103, v91, v101, -v111
	v_pk_fma_f32 v[100:101], v[90:91], v[100:101], v[110:111] op_sel_hi:[1,0,1]
	v_lshlrev_b64 v[104:105], 10, v[106:107]
	v_lshlrev_b64 v[110:111], 10, v[108:109]
	v_lshlrev_b64 v[108:109], 10, v[142:143]
	ds_write_b128 v117, v[48:51]
	ds_write_b128 v117, v[52:55] offset:64
	ds_write_b128 v117, v[56:59] offset:128
	ds_write_b128 v117, v[60:63] offset:192
	ds_write_b128 v117, v[64:67] offset:256
	ds_write_b128 v117, v[68:71] offset:320
	ds_write_b128 v117, v[72:75] offset:384
	ds_write_b128 v117, v[76:79] offset:448
	v_mov_b32_e32 v103, v101
	v_lshl_add_u64 v[100:101], v[98:99], 0, v[104:105]
	v_lshlrev_b64 v[106:107], 10, v[144:145]
	s_waitcnt lgkmcnt(0)
; __device__ __forceinline__ void ssm_pass2(LAS unsigned char* lds, const bf16_t* US, const float* SST, bf16_t* YB, const float* ABAR, const bf16_t* BBH, const bf16_t* BBL, const bf16_t* CMH, const bf16_t* CML, const float* dco, int gw, int NGW, int lane, int wave) {
;     ...
;         for (int grp = 0; grp < 16; ++grp) { const int tok = tokc + grp * 16;
;             ssm_bu_tile(S, uh, tile, lane);
;             if (grp < 15) ssm_u_load(uh, US, tok + 16, g, lane);
;             float ud[4];
; #pragma unroll
;             for (int i = 0; i < 4; ++i) ud[i] = bf_lo((unsigned)US[(size_t)(tok + 4 * fq + i) * SSMW + g * 16 + fr]);
;             float br[16], bi[16];
; #pragma unroll
;             for (int t = 0; t < 16; ++t) { br[t] = tile[t * TSTR + lane]; bi[t] = tile[t * TSTR + 64 + lane]; }
;             asm volatile("s_waitcnt lgkmcnt(0)" ::: "memory");
; #pragma unroll
;             for (int t = 0; t < 16; ++t) { const float nr = S.ar * xr - S.ai * xi + br[t], ni = S.ar * xi + S.ai * xr + bi[t]; xr = nr; xi = ni; br[t] = xr; bi[t] = xi; }
; #pragma unroll
;             for (int t = 0; t < 16; ++t) { tile[t * TSTR + lane] = br[t]; tile[t * TSTR + 64 + lane] = bi[t]; }
	global_load_dwordx4 v[48:51], v[100:101], off
	v_add_u32_e32 v138, 0xd0, v119
	v_add_u32_e32 v139, 0xe0, v119
	v_add_u32_e32 v140, 0xf0, v119
	ds_read2st64_b32 v[52:53], v119 offset1:1
	ds_read2_b32 v[54:55], v119 offset0:132 offset1:196
	ds_read2st64_b32 v[56:57], v127 offset0:4 offset1:5
	ds_read2st64_b32 v[58:59], v128 offset0:6 offset1:7
	ds_read2st64_b32 v[60:61], v129 offset0:8 offset1:9
	ds_read2st64_b32 v[62:63], v130 offset0:10 offset1:11
	ds_read2st64_b32 v[64:65], v131 offset0:12 offset1:13
	ds_read2st64_b32 v[66:67], v132 offset0:14 offset1:15
	ds_read2st64_b32 v[68:69], v133 offset0:16 offset1:17
	ds_read2st64_b32 v[70:71], v134 offset0:18 offset1:19
	ds_read2st64_b32 v[72:73], v135 offset0:20 offset1:21
	ds_read2st64_b32 v[74:75], v136 offset0:22 offset1:23
	ds_read2st64_b32 v[76:77], v137 offset0:24 offset1:25
	ds_read2st64_b32 v[78:79], v138 offset0:26 offset1:27
	ds_read2st64_b32 v[100:101], v139 offset0:28 offset1:29
	ds_read2st64_b32 v[104:105], v140 offset0:30 offset1:31
	s_waitcnt lgkmcnt(14)
	v_pk_add_f32 v[52:53], v[102:103], v[52:53]
	v_lshl_add_u64 v[150:151], v[92:93], 0, v[106:107]
	v_pk_mul_f32 v[102:103], v[90:91], v[52:53]
	v_pk_mul_f32 v[106:107], v[94:95], v[52:53]
	s_waitcnt lgkmcnt(0)
	ds_write2st64_b32 v119, v52, v53 offset1:1
	v_sub_f32_e32 v52, v102, v103
	v_add_f32_e32 v53, v106, v107
	v_add_f32_e32 v52, v54, v52
	v_add_f32_e32 v54, v55, v53
	v_pk_mul_f32 v[102:103], v[94:95], v[54:55] op_sel_hi:[1,0]
	ds_write2_b32 v119, v52, v54 offset0:132 offset1:196
	v_pk_fma_f32 v[54:55], v[90:91], v[52:53], v[102:103] neg_lo:[0,0,1] neg_hi:[0,0,1]
	v_pk_fma_f32 v[52:53], v[90:91], v[52:53], v[102:103] op_sel_hi:[1,0,1]
	v_lshl_add_u64 v[148:149], v[92:93], 0, v[108:109]
	v_mov_b32_e32 v55, v53
	s_waitcnt lgkmcnt(14)
	v_pk_add_f32 v[52:53], v[56:57], v[54:55]
	ds_write2st64_b32 v127, v52, v53 offset0:4 offset1:5
	v_pk_mul_f32 v[56:57], v[90:91], v[52:53] op_sel:[0,1] op_sel_hi:[1,0]
	v_pk_mul_f32 v[54:55], v[90:91], v[52:53]
	v_add_f32_e32 v53, v56, v57
	v_sub_f32_e32 v52, v54, v55
	v_add_f32_e32 v54, v59, v53
	v_add_f32_e32 v52, v58, v52
	v_pk_mul_f32 v[56:57], v[94:95], v[54:55] op_sel_hi:[1,0]
	ds_write2st64_b32 v128, v52, v54 offset0:6 offset1:7
	v_pk_fma_f32 v[54:55], v[90:91], v[52:53], v[56:57] neg_lo:[0,0,1] neg_hi:[0,0,1]
	v_pk_fma_f32 v[52:53], v[90:91], v[52:53], v[56:57] op_sel_hi:[1,0,1]
	v_lshl_add_u64 v[110:111], v[92:93], 0, v[110:111]
	v_mov_b32_e32 v55, v53
	s_waitcnt lgkmcnt(14)
	v_pk_add_f32 v[52:53], v[60:61], v[54:55]
	ds_write2st64_b32 v129, v52, v53 offset0:8 offset1:9
	v_pk_mul_f32 v[56:57], v[90:91], v[52:53] op_sel:[0,1] op_sel_hi:[1,0]
	v_pk_mul_f32 v[54:55], v[90:91], v[52:53]
	v_add_f32_e32 v53, v56, v57
	v_sub_f32_e32 v52, v54, v55
	v_add_f32_e32 v54, v63, v53
	v_add_f32_e32 v52, v62, v52
	v_pk_mul_f32 v[56:57], v[94:95], v[54:55] op_sel_hi:[1,0]
	ds_write2st64_b32 v130, v52, v54 offset0:10 offset1:11
	v_pk_fma_f32 v[54:55], v[90:91], v[52:53], v[56:57] neg_lo:[0,0,1] neg_hi:[0,0,1]
	v_pk_fma_f32 v[52:53], v[90:91], v[52:53], v[56:57] op_sel_hi:[1,0,1]
	v_lshl_add_u64 v[112:113], v[92:93], 0, v[112:113]
	v_mov_b32_e32 v55, v53
	s_waitcnt lgkmcnt(14)
	v_pk_add_f32 v[52:53], v[64:65], v[54:55]
	ds_write2st64_b32 v131, v52, v53 offset0:12 offset1:13
	v_pk_mul_f32 v[56:57], v[90:91], v[52:53] op_sel:[0,1] op_sel_hi:[1,0]
	v_pk_mul_f32 v[54:55], v[90:91], v[52:53]
	v_add_f32_e32 v53, v56, v57
	v_sub_f32_e32 v52, v54, v55
	v_add_f32_e32 v54, v67, v53
	v_add_f32_e32 v52, v66, v52
	v_pk_mul_f32 v[56:57], v[94:95], v[54:55] op_sel_hi:[1,0]
	ds_write2st64_b32 v132, v52, v54 offset0:14 offset1:15
	v_pk_fma_f32 v[54:55], v[90:91], v[52:53], v[56:57] neg_lo:[0,0,1] neg_hi:[0,0,1]
	v_pk_fma_f32 v[52:53], v[90:91], v[52:53], v[56:57] op_sel_hi:[1,0,1]
	s_add_i32 s20, s20, 16
	v_mov_b32_e32 v55, v53
	s_waitcnt lgkmcnt(14)
	v_pk_add_f32 v[52:53], v[68:69], v[54:55]
	ds_write2st64_b32 v133, v52, v53 offset0:16 offset1:17
	v_pk_mul_f32 v[56:57], v[90:91], v[52:53] op_sel:[0,1] op_sel_hi:[1,0]
	v_pk_mul_f32 v[54:55], v[90:91], v[52:53]
	v_add_f32_e32 v53, v56, v57
	v_sub_f32_e32 v52, v54, v55
	v_add_f32_e32 v54, v71, v53
	v_add_f32_e32 v52, v70, v52
	v_pk_mul_f32 v[56:57], v[94:95], v[54:55] op_sel_hi:[1,0]
	ds_write2st64_b32 v134, v52, v54 offset0:18 offset1:19
	v_pk_fma_f32 v[54:55], v[90:91], v[52:53], v[56:57] neg_lo:[0,0,1] neg_hi:[0,0,1]
	v_pk_fma_f32 v[52:53], v[90:91], v[52:53], v[56:57] op_sel_hi:[1,0,1]
	s_cmpk_eq_i32 s20, 0xf0
	v_mov_b32_e32 v55, v53
	s_waitcnt lgkmcnt(14)
	v_pk_add_f32 v[52:53], v[72:73], v[54:55]
	ds_write2st64_b32 v135, v52, v53 offset0:20 offset1:21
	v_pk_mul_f32 v[56:57], v[90:91], v[52:53] op_sel:[0,1] op_sel_hi:[1,0]
	v_pk_mul_f32 v[54:55], v[90:91], v[52:53]
	v_add_f32_e32 v53, v56, v57
	v_sub_f32_e32 v52, v54, v55
	v_add_f32_e32 v54, v75, v53
	v_add_f32_e32 v52, v74, v52
	v_pk_mul_f32 v[56:57], v[94:95], v[54:55] op_sel_hi:[1,0]
	ds_write2st64_b32 v136, v52, v54 offset0:22 offset1:23
	v_pk_fma_f32 v[54:55], v[90:91], v[52:53], v[56:57] neg_lo:[0,0,1] neg_hi:[0,0,1]
	v_pk_fma_f32 v[52:53], v[90:91], v[52:53], v[56:57] op_sel_hi:[1,0,1]
	s_nop 0
	v_mov_b32_e32 v55, v53
	s_waitcnt lgkmcnt(14)
	v_pk_add_f32 v[52:53], v[76:77], v[54:55]
	ds_write2st64_b32 v137, v52, v53 offset0:24 offset1:25
	v_pk_mul_f32 v[56:57], v[90:91], v[52:53] op_sel:[0,1] op_sel_hi:[1,0]
	v_pk_mul_f32 v[54:55], v[90:91], v[52:53]
	v_add_f32_e32 v53, v56, v57
	v_sub_f32_e32 v52, v54, v55
	v_add_f32_e32 v54, v79, v53
	v_add_f32_e32 v52, v78, v52
	v_pk_mul_f32 v[56:57], v[94:95], v[54:55] op_sel_hi:[1,0]
	ds_write2st64_b32 v138, v52, v54 offset0:26 offset1:27
	v_pk_fma_f32 v[54:55], v[90:91], v[52:53], v[56:57] neg_lo:[0,0,1] neg_hi:[0,0,1]
	v_pk_fma_f32 v[52:53], v[90:91], v[52:53], v[56:57] op_sel_hi:[1,0,1]
	s_nop 0
	v_mov_b32_e32 v55, v53
	s_waitcnt lgkmcnt(14)
; __device__ __forceinline__ unsigned cvt_pk_bf16(float lo, float hi) { unsigned r; asm volatile("v_cvt_pk_bf16_f32 %0, %1, %2" : "=v"(r) : "v"(lo), "v"(hi)); return r; }
; #define LAS __attribute__((address_space(3)))
; __device__ __forceinline__ float gelu_tanh(float x) { const float z = 0.7978845608028654f * (x + 0.044715f * x * x * x); const float e = __builtin_amdgcn_exp2f(2.f * LOG2E * z); return 0.5f * x * (2.f - 2.f * __builtin_amdgcn_rcpf(1.f + e)); }
; __device__ __forceinline__ void ssm_pass2(LAS unsigned char* lds, const bf16_t* US, const float* SST, bf16_t* YB, const float* ABAR, const bf16_t* BBH, const bf16_t* BBL, const bf16_t* CMH, const bf16_t* CML, const float* dco, int gw, int NGW, int lane, int wave) {
;     ...
;             for (int t = 0; t < 16; ++t) { const float nr = S.ar * xr - S.ai * xi + br[t], ni = S.ar * xi + S.ai * xr + bi[t]; xr = nr; xi = ni; br[t] = xr; bi[t] = xi; }
; #pragma unroll
;             for (int t = 0; t < 16; ++t) { tile[t * TSTR + lane] = br[t]; tile[t * TSTR + 64 + lane] = bi[t]; }
;             asm volatile("s_waitcnt lgkmcnt(0)" ::: "memory");
;             f32x4 acc = {0.f, 0.f, 0.f, 0.f}, acc2 = {0.f, 0.f, 0.f, 0.f};
;             f32x4 xa[4][2];
; #pragma unroll
;             for (int ks = 0; ks < 4; ++ks) { xa[ks][0] = *(const LAS f32x4*)(tile + fr * TSTR + ks * 32 + fq * 8); xa[ks][1] = *(const LAS f32x4*)(tile + fr * TSTR + ks * 32 + fq * 8 + 4); }
; #pragma unroll
;             for (int ks = 0; ks < 4; ++ks) { const f32x4 x0 = xa[ks][0], x1 = xa[ks][1]; u32x4 h;
;                 h.x = cvt_pk_bf16(x0[0], x0[1]); h.y = cvt_pk_bf16(x0[2], x0[3]); h.z = cvt_pk_bf16(x1[0], x1[1]); h.w = cvt_pk_bf16(x1[2], x1[3]);
;                 const bf16x8 xh = __builtin_bit_cast(bf16x8, h);
;                 if (ks & 1) acc2 = __builtin_amdgcn_mfma_f32_16x16x32_bf16(xh, ch[ks], acc2, 0, 0, 0); else acc = __builtin_amdgcn_mfma_f32_16x16x32_bf16(xh, ch[ks], acc, 0, 0, 0); }
;             acc = acc + acc2;
; #pragma unroll
;             for (int i = 0; i < 4; ++i) { const float y = acc[i] + dh * ud[i];
;                 const unsigned w = cvt_pk_bf16(gelu_tanh(y), 0.f); YB[(size_t)(tok + 4 * fq + i) * SSMW + g * 16 + fr] = (bf16_t)(w & 0xffffu); }
;             asm volatile("s_waitcnt lgkmcnt(0)" ::: "memory");
;         }
	v_pk_add_f32 v[52:53], v[100:101], v[54:55]
	ds_write2st64_b32 v139, v52, v53 offset0:28 offset1:29
	v_pk_mul_f32 v[54:55], v[90:91], v[52:53]
	v_pk_mul_f32 v[56:57], v[90:91], v[52:53] op_sel:[0,1] op_sel_hi:[1,0]
	v_sub_f32_e32 v52, v54, v55
	v_add_f32_e32 v53, v56, v57
	v_add_f32_e32 v100, v104, v52
	v_add_f32_e32 v76, v105, v53
	ds_write2st64_b32 v140, v100, v76 offset0:30 offset1:31
	s_waitcnt lgkmcnt(0)
	ds_read_b128 v[52:55], v123
	ds_read_b128 v[56:59], v123 offset:16
	ds_read_b128 v[60:63], v123 offset:128
	ds_read_b128 v[64:67], v123 offset:144
	ds_read_b128 v[68:71], v123 offset:256
	ds_read_b128 v[72:75], v123 offset:272
	ds_read_b128 v[102:105], v123 offset:384
	ds_read_b128 v[106:109], v123 offset:400
	s_waitcnt lgkmcnt(7)
	v_cvt_pk_bf16_f32 v52, v52, v53
	v_cvt_pk_bf16_f32 v53, v54, v55
	s_waitcnt lgkmcnt(6)
	v_cvt_pk_bf16_f32 v54, v56, v57
	v_cvt_pk_bf16_f32 v55, v58, v59
	s_waitcnt lgkmcnt(5)
	v_cvt_pk_bf16_f32 v56, v60, v61
	v_cvt_pk_bf16_f32 v57, v62, v63
	s_waitcnt lgkmcnt(4)
	v_cvt_pk_bf16_f32 v58, v64, v65
	v_cvt_pk_bf16_f32 v59, v66, v67
	s_waitcnt lgkmcnt(3)
	v_cvt_pk_bf16_f32 v60, v68, v69
	v_mfma_f32_16x16x32_bf16 v[52:55], v[52:55], v[12:15], 0
	v_cvt_pk_bf16_f32 v61, v70, v71
	s_waitcnt lgkmcnt(2)
	v_cvt_pk_bf16_f32 v62, v72, v73
	v_cvt_pk_bf16_f32 v63, v74, v75
	v_mfma_f32_16x16x32_bf16 v[56:59], v[56:59], v[8:11], 0
	s_waitcnt lgkmcnt(1)
	v_cvt_pk_bf16_f32 v64, v102, v103
	v_cvt_pk_bf16_f32 v65, v104, v105
	s_waitcnt lgkmcnt(0)
	v_cvt_pk_bf16_f32 v66, v106, v107
	v_mfma_f32_16x16x32_bf16 v[52:55], v[60:63], v[4:7], v[52:55]
	v_cvt_pk_bf16_f32 v67, v108, v109
	s_nop 0
	v_mfma_f32_16x16x32_bf16 v[56:59], v[64:67], v[0:3], v[56:59]
	s_nop 7
	v_pk_add_f32 v[52:53], v[52:53], v[56:57]
	v_fma_f32 v52, v124, v156, v52
	v_mul_f32_e32 v56, 0x3d372713, v52
	v_pk_add_f32 v[54:55], v[54:55], v[58:59]
	v_fmac_f32_e32 v53, v124, v157
	v_mul_f32_e32 v56, v52, v56
	v_fma_f32 v54, v124, v158, v54
	v_mul_f32_e32 v57, 0.5, v52
	v_mul_f32_e32 v58, 0x3d372713, v53
	v_fma_f32 v52, v52, v56, v52
	v_fmac_f32_e32 v55, v124, v159
	v_mul_f32_e32 v60, 0x3d372713, v54
	v_mul_f32_e32 v58, v53, v58
	v_mul_f32_e32 v52, 0x3f4c422a, v52
	v_mul_f32_e32 v59, 0.5, v53
	v_mul_f32_e32 v62, 0x3d372713, v55
	v_mul_f32_e32 v60, v54, v60
	v_fma_f32 v53, v53, v58, v53
	v_mul_f32_e32 v52, 0x4038aa3b, v52
	v_mul_f32_e32 v61, 0.5, v54
	v_mul_f32_e32 v62, v55, v62
	v_fma_f32 v54, v54, v60, v54
	v_mul_f32_e32 v53, 0x3f4c422a, v53
	v_exp_f32_e32 v52, v52
	v_mul_f32_e32 v63, 0.5, v55
	v_fma_f32 v55, v55, v62, v55
	v_mul_f32_e32 v54, 0x3f4c422a, v54
	v_mul_f32_e32 v53, 0x4038aa3b, v53
	v_mul_f32_e32 v55, 0x3f4c422a, v55
	v_mul_f32_e32 v54, 0x4038aa3b, v54
	v_exp_f32_e32 v53, v53
	v_mul_f32_e32 v55, 0x4038aa3b, v55
	v_exp_f32_e32 v54, v54
	v_exp_f32_e32 v55, v55
	v_add_f32_e32 v52, 1.0, v52
	v_rcp_f32_e32 v52, v52
	v_add_f32_e32 v53, 1.0, v53
	v_add_f32_e32 v54, 1.0, v54
	v_rcp_f32_e32 v53, v53
	v_add_f32_e32 v55, 1.0, v55
	v_rcp_f32_e32 v54, v54
	v_rcp_f32_e32 v55, v55
	v_fma_f32 v52, v52, -2.0, 2.0
	v_mul_f32_e32 v52, v57, v52
	v_fma_f32 v53, v53, -2.0, 2.0
	v_cvt_pk_bf16_f32 v52, v52, v81
	v_fma_f32 v54, v54, -2.0, 2.0
	v_mul_f32_e32 v53, v59, v53
	global_store_short v[110:111], v52, off
	v_cvt_pk_bf16_f32 v52, v53, v81
	v_fma_f32 v55, v55, -2.0, 2.0
	v_mul_f32_e32 v54, v61, v54
	global_store_short v[112:113], v52, off
	v_cvt_pk_bf16_f32 v52, v54, v81
	v_mul_f32_e32 v55, v63, v55
	global_store_short v[148:149], v52, off
	v_cvt_pk_bf16_f32 v52, v55, v81
	global_store_short v[150:151], v52, off
	s_waitcnt lgkmcnt(0)
	s_waitcnt vmcnt(4)
	s_cbranch_scc0 .LBB0_550
	v_cndmask_b32_e64 v51, v51, 0, s[6:7]
	v_cndmask_b32_e64 v50, v50, 0, s[6:7]
	v_cndmask_b32_e64 v49, v49, 0, s[6:7]
	v_cndmask_b32_e64 v48, v48, 0, s[6:7]
	v_mul_f32_e32 v59, v91, v100
	v_fmac_f32_e32 v59, v90, v76
	v_mfma_f32_16x16x32_bf16 v[16:19], v[16:19], v[48:51], 0
	s_add_i32 s70, s70, s33
	s_add_i32 s68, s68, s69
	s_cmpk_gt_i32 s70, 0xfff
	v_mfma_f32_16x16x32_bf16 v[20:23], v[20:23], v[48:51], 0
	v_mfma_f32_16x16x32_bf16 v[24:27], v[24:27], v[48:51], 0
	s_nop 2
	ds_write_b128 v117, v[16:19]
	v_mfma_f32_16x16x32_bf16 v[28:31], v[28:31], v[48:51], 0
	s_nop 1
	ds_write_b128 v117, v[20:23] offset:64
	ds_write_b128 v117, v[24:27] offset:128
	s_nop 3
	ds_write_b128 v117, v[28:31] offset:192
	v_or_b32_e32 v28, s59, v118
	v_mfma_f32_16x16x32_bf16 v[32:35], v[32:35], v[48:51], 0
	v_mfma_f32_16x16x32_bf16 v[16:19], v[36:39], v[48:51], 0
	v_mfma_f32_16x16x32_bf16 v[20:23], v[40:43], v[48:51], 0
	s_nop 5
	ds_write_b128 v117, v[32:35] offset:256
	ds_write_b128 v117, v[16:19] offset:320
	ds_write_b128 v117, v[20:23] offset:384
	v_mfma_f32_16x16x32_bf16 v[16:19], v[44:47], v[48:51], 0
	s_nop 7
	ds_write_b128 v117, v[16:19] offset:448
	v_or_b32_e32 v16, 0xf0, v28
	v_ashrrev_i32_e32 v17, 31, v16
	v_lshlrev_b64 v[20:21], 10, v[16:17]
	v_or_b32_e32 v16, 0xf1, v28
	v_ashrrev_i32_e32 v17, 31, v16
	v_lshlrev_b64 v[18:19], 10, v[16:17]
	v_or_b32_e32 v16, 0xf2, v28
	v_ashrrev_i32_e32 v17, 31, v16
	s_waitcnt lgkmcnt(0)
; __device__ __forceinline__ void ssm_pass2(LAS unsigned char* lds, const bf16_t* US, const float* SST, bf16_t* YB, const float* ABAR, const bf16_t* BBH, const bf16_t* BBL, const bf16_t* CMH, const bf16_t* CML, const float* dco, int gw, int NGW, int lane, int wave) {
;     ...
;         for (int grp = 0; grp < 16; ++grp) { const int tok = tokc + grp * 16;
;             ssm_bu_tile(S, uh, tile, lane);
;             if (grp < 15) ssm_u_load(uh, US, tok + 16, g, lane);
;             float ud[4];
; #pragma unroll
;             for (int i = 0; i < 4; ++i) ud[i] = bf_lo((unsigned)US[(size_t)(tok + 4 * fq + i) * SSMW + g * 16 + fr]);
;             float br[16], bi[16];
; #pragma unroll
;             for (int t = 0; t < 16; ++t) { br[t] = tile[t * TSTR + lane]; bi[t] = tile[t * TSTR + 64 + lane]; }
;             asm volatile("s_waitcnt lgkmcnt(0)" ::: "memory");
; #pragma unroll
;             for (int t = 0; t < 16; ++t) { const float nr = S.ar * xr - S.ai * xi + br[t], ni = S.ar * xi + S.ai * xr + bi[t]; xr = nr; xi = ni; br[t] = xr; bi[t] = xi; }
	v_lshl_add_u64 v[22:23], v[96:97], 0, v[20:21]
	v_lshlrev_b64 v[16:17], 10, v[16:17]
	v_lshl_add_u64 v[24:25], v[96:97], 0, v[18:19]
	v_lshl_add_u64 v[26:27], v[96:97], 0, v[16:17]
	global_load_ushort v56, v[22:23], off
	global_load_ushort v57, v[24:25], off
	global_load_ushort v58, v[26:27], off
	v_mul_f32_e32 v23, v91, v76
	v_or_b32_e32 v22, 0xf3, v28
	v_fma_f32 v60, v90, v100, -v23
	v_ashrrev_i32_e32 v23, 31, v22
	v_lshlrev_b64 v[22:23], 10, v[22:23]
	v_lshl_add_u64 v[24:25], v[96:97], 0, v[22:23]
	global_load_ushort v61, v[24:25], off
	ds_read2st64_b32 v[24:25], v119 offset1:1
	ds_read2_b32 v[26:27], v119 offset0:132 offset1:196
	ds_read2st64_b32 v[28:29], v127 offset0:4 offset1:5
	ds_read2st64_b32 v[30:31], v128 offset0:6 offset1:7
	ds_read2st64_b32 v[32:33], v129 offset0:8 offset1:9
	ds_read2st64_b32 v[34:35], v130 offset0:10 offset1:11
	ds_read2st64_b32 v[36:37], v131 offset0:12 offset1:13
	ds_read2st64_b32 v[38:39], v132 offset0:14 offset1:15
	ds_read2st64_b32 v[40:41], v133 offset0:16 offset1:17
	ds_read2st64_b32 v[42:43], v134 offset0:18 offset1:19
	ds_read2st64_b32 v[44:45], v135 offset0:20 offset1:21
	ds_read2st64_b32 v[46:47], v136 offset0:22 offset1:23
	ds_read2st64_b32 v[48:49], v137 offset0:24 offset1:25
	ds_read2st64_b32 v[50:51], v138 offset0:26 offset1:27
	ds_read2st64_b32 v[52:53], v139 offset0:28 offset1:29
	ds_read2st64_b32 v[54:55], v140 offset0:30 offset1:31
	s_waitcnt lgkmcnt(14)
	v_add_f32_e32 v25, v59, v25
	v_add_f32_e32 v24, v60, v24
	v_mul_f32_e32 v60, v90, v25
	v_mul_f32_e32 v59, v91, v25
	v_fmac_f32_e32 v60, v91, v24
	v_fma_f32 v59, v90, v24, -v59
	v_add_f32_e32 v27, v27, v60
	v_add_f32_e32 v26, v26, v59
	v_mul_f32_e32 v59, v91, v27
	v_mul_f32_e32 v60, v91, v26
	v_fma_f32 v59, v90, v26, -v59
	v_fmac_f32_e32 v60, v90, v27
	s_waitcnt lgkmcnt(13)
	v_add_f32_e32 v28, v28, v59
	v_add_f32_e32 v29, v29, v60
	v_mul_f32_e32 v60, v91, v28
	v_mul_f32_e32 v59, v91, v29
	v_fmac_f32_e32 v60, v90, v29
	v_fma_f32 v59, v90, v28, -v59
	s_waitcnt lgkmcnt(12)
	v_add_f32_e32 v31, v31, v60
	v_add_f32_e32 v30, v30, v59
	v_mul_f32_e32 v59, v91, v31
	v_fma_f32 v59, v90, v30, -v59
	s_waitcnt lgkmcnt(11)
	v_add_f32_e32 v32, v32, v59
	v_mul_f32_e32 v59, v91, v30
	v_fmac_f32_e32 v59, v90, v31
	v_add_f32_e32 v33, v33, v59
	v_mul_f32_e32 v59, v91, v33
	v_fma_f32 v59, v90, v32, -v59
	s_waitcnt lgkmcnt(10)
	v_add_f32_e32 v34, v34, v59
	v_mul_f32_e32 v59, v91, v32
	v_fmac_f32_e32 v59, v90, v33
	v_add_f32_e32 v35, v35, v59
	v_mul_f32_e32 v59, v91, v35
	v_fma_f32 v59, v90, v34, -v59
	s_waitcnt lgkmcnt(9)
	v_add_f32_e32 v36, v36, v59
	v_mul_f32_e32 v59, v91, v34
	v_fmac_f32_e32 v59, v90, v35
	v_add_f32_e32 v37, v37, v59
	v_mul_f32_e32 v59, v91, v37
	v_fma_f32 v59, v90, v36, -v59
	s_waitcnt lgkmcnt(8)
	v_add_f32_e32 v38, v38, v59
	v_mul_f32_e32 v59, v91, v36
	v_fmac_f32_e32 v59, v90, v37
	v_add_f32_e32 v39, v39, v59
	v_mul_f32_e32 v59, v91, v39
	v_fma_f32 v59, v90, v38, -v59
	s_waitcnt lgkmcnt(7)
	v_add_f32_e32 v40, v40, v59
	v_mul_f32_e32 v59, v91, v38
	v_fmac_f32_e32 v59, v90, v39
	v_add_f32_e32 v41, v41, v59
	v_mul_f32_e32 v59, v91, v41
	v_fma_f32 v59, v90, v40, -v59
	s_waitcnt lgkmcnt(6)
	v_add_f32_e32 v42, v42, v59
	v_mul_f32_e32 v59, v91, v40
	v_fmac_f32_e32 v59, v90, v41
	v_add_f32_e32 v43, v43, v59
	v_mul_f32_e32 v59, v91, v43
	v_fma_f32 v59, v90, v42, -v59
	s_waitcnt lgkmcnt(5)
	v_add_f32_e32 v44, v44, v59
	v_mul_f32_e32 v59, v91, v42
	v_fmac_f32_e32 v59, v90, v43
	v_add_f32_e32 v45, v45, v59
	v_mul_f32_e32 v59, v91, v45
	v_fma_f32 v59, v90, v44, -v59
	s_waitcnt lgkmcnt(4)
	v_add_f32_e32 v46, v46, v59
	v_mul_f32_e32 v59, v91, v44
	v_fmac_f32_e32 v59, v90, v45
	v_add_f32_e32 v47, v47, v59
	v_mul_f32_e32 v59, v91, v47
	v_fma_f32 v59, v90, v46, -v59
	s_waitcnt lgkmcnt(3)
	v_add_f32_e32 v48, v48, v59
	v_mul_f32_e32 v59, v91, v46
	v_fmac_f32_e32 v59, v90, v47
	v_add_f32_e32 v49, v49, v59
	v_mul_f32_e32 v59, v91, v49
	v_fma_f32 v59, v90, v48, -v59
	s_waitcnt lgkmcnt(2)
	v_add_f32_e32 v50, v50, v59
	v_mul_f32_e32 v59, v91, v48
	v_fmac_f32_e32 v59, v90, v49
	v_add_f32_e32 v51, v51, v59
	v_mul_f32_e32 v59, v91, v51
	v_fma_f32 v59, v90, v50, -v59
	s_waitcnt lgkmcnt(1)
	v_add_f32_e32 v52, v52, v59
	v_mul_f32_e32 v59, v91, v50
	v_fmac_f32_e32 v59, v90, v51
	v_add_f32_e32 v53, v53, v59
	v_mul_f32_e32 v59, v91, v53
	v_fma_f32 v59, v90, v52, -v59
	s_waitcnt lgkmcnt(0)
; __device__ __forceinline__ unsigned cvt_pk_bf16(float lo, float hi) { unsigned r; asm volatile("v_cvt_pk_bf16_f32 %0, %1, %2" : "=v"(r) : "v"(lo), "v"(hi)); return r; }
; #define LAS __attribute__((address_space(3)))
; __device__ __forceinline__ float gelu_tanh(float x) { const float z = 0.7978845608028654f * (x + 0.044715f * x * x * x); const float e = __builtin_amdgcn_exp2f(2.f * LOG2E * z); return 0.5f * x * (2.f - 2.f * __builtin_amdgcn_rcpf(1.f + e)); }
; __device__ __forceinline__ void ssm_pass2(LAS unsigned char* lds, const bf16_t* US, const float* SST, bf16_t* YB, const float* ABAR, const bf16_t* BBH, const bf16_t* BBL, const bf16_t* CMH, const bf16_t* CML, const float* dco, int gw, int NGW, int lane, int wave) {
;     ...
;             for (int t = 0; t < 16; ++t) { const float nr = S.ar * xr - S.ai * xi + br[t], ni = S.ar * xi + S.ai * xr + bi[t]; xr = nr; xi = ni; br[t] = xr; bi[t] = xi; }
; #pragma unroll
;             for (int t = 0; t < 16; ++t) { tile[t * TSTR + lane] = br[t]; tile[t * TSTR + 64 + lane] = bi[t]; }
;             asm volatile("s_waitcnt lgkmcnt(0)" ::: "memory");
;             f32x4 acc = {0.f, 0.f, 0.f, 0.f}, acc2 = {0.f, 0.f, 0.f, 0.f};
;             f32x4 xa[4][2];
; #pragma unroll
;             for (int ks = 0; ks < 4; ++ks) { xa[ks][0] = *(const LAS f32x4*)(tile + fr * TSTR + ks * 32 + fq * 8); xa[ks][1] = *(const LAS f32x4*)(tile + fr * TSTR + ks * 32 + fq * 8 + 4); }
; #pragma unroll
;             for (int ks = 0; ks < 4; ++ks) { const f32x4 x0 = xa[ks][0], x1 = xa[ks][1]; u32x4 h;
;                 h.x = cvt_pk_bf16(x0[0], x0[1]); h.y = cvt_pk_bf16(x0[2], x0[3]); h.z = cvt_pk_bf16(x1[0], x1[1]); h.w = cvt_pk_bf16(x1[2], x1[3]);
;                 const bf16x8 xh = __builtin_bit_cast(bf16x8, h);
;                 if (ks & 1) acc2 = __builtin_amdgcn_mfma_f32_16x16x32_bf16(xh, ch[ks], acc2, 0, 0, 0); else acc = __builtin_amdgcn_mfma_f32_16x16x32_bf16(xh, ch[ks], acc, 0, 0, 0); }
;             acc = acc + acc2;
; #pragma unroll
;             for (int i = 0; i < 4; ++i) { const float y = acc[i] + dh * ud[i];
;                 const unsigned w = cvt_pk_bf16(gelu_tanh(y), 0.f); YB[(size_t)(tok + 4 * fq + i) * SSMW + g * 16 + fr] = (bf16_t)(w & 0xffffu); }
;             asm volatile("s_waitcnt lgkmcnt(0)" ::: "memory");
;         }
	v_add_f32_e32 v54, v54, v59
	v_mul_f32_e32 v59, v91, v52
	v_fmac_f32_e32 v59, v90, v53
	s_waitcnt lgkmcnt(0)
	v_add_f32_e32 v55, v55, v59
	ds_write2st64_b32 v119, v24, v25 offset1:1
	ds_write2_b32 v119, v26, v27 offset0:132 offset1:196
	ds_write2st64_b32 v127, v28, v29 offset0:4 offset1:5
	ds_write2st64_b32 v128, v30, v31 offset0:6 offset1:7
	ds_write2st64_b32 v129, v32, v33 offset0:8 offset1:9
	ds_write2st64_b32 v130, v34, v35 offset0:10 offset1:11
	ds_write2st64_b32 v131, v36, v37 offset0:12 offset1:13
	ds_write2st64_b32 v132, v38, v39 offset0:14 offset1:15
	ds_write2st64_b32 v133, v40, v41 offset0:16 offset1:17
	ds_write2st64_b32 v134, v42, v43 offset0:18 offset1:19
	ds_write2st64_b32 v135, v44, v45 offset0:20 offset1:21
	ds_write2st64_b32 v136, v46, v47 offset0:22 offset1:23
	ds_write2st64_b32 v137, v48, v49 offset0:24 offset1:25
	ds_write2st64_b32 v138, v50, v51 offset0:26 offset1:27
	ds_write2st64_b32 v139, v52, v53 offset0:28 offset1:29
	ds_write2st64_b32 v140, v54, v55 offset0:30 offset1:31
	s_waitcnt lgkmcnt(0)
	ds_read_b128 v[24:27], v123
	ds_read_b128 v[28:31], v123 offset:16
	ds_read_b128 v[32:35], v123 offset:128
	ds_read_b128 v[36:39], v123 offset:144
	ds_read_b128 v[40:43], v123 offset:256
	ds_read_b128 v[44:47], v123 offset:272
	ds_read_b128 v[48:51], v123 offset:384
	ds_read_b128 v[52:55], v123 offset:400
	s_waitcnt lgkmcnt(7)
	v_cvt_pk_bf16_f32 v24, v24, v25
	v_cvt_pk_bf16_f32 v25, v26, v27
	s_waitcnt lgkmcnt(6)
	v_cvt_pk_bf16_f32 v26, v28, v29
	v_cvt_pk_bf16_f32 v27, v30, v31
	s_waitcnt vmcnt(3)
	v_lshlrev_b32_e32 v56, 16, v56
	v_mfma_f32_16x16x32_bf16 v[12:15], v[24:27], v[12:15], 0
	s_waitcnt lgkmcnt(5)
	v_cvt_pk_bf16_f32 v24, v32, v33
	v_cvt_pk_bf16_f32 v25, v34, v35
	s_waitcnt lgkmcnt(4)
	v_cvt_pk_bf16_f32 v26, v36, v37
	v_cvt_pk_bf16_f32 v27, v38, v39
	s_waitcnt vmcnt(2)
	v_lshlrev_b32_e32 v57, 16, v57
	v_mfma_f32_16x16x32_bf16 v[8:11], v[24:27], v[8:11], 0
	s_waitcnt lgkmcnt(3)
	v_cvt_pk_bf16_f32 v24, v40, v41
	v_cvt_pk_bf16_f32 v25, v42, v43
	s_waitcnt lgkmcnt(2)
	v_cvt_pk_bf16_f32 v26, v44, v45
	v_cvt_pk_bf16_f32 v27, v46, v47
	s_waitcnt vmcnt(1)
	v_lshlrev_b32_e32 v58, 16, v58
	v_mfma_f32_16x16x32_bf16 v[4:7], v[24:27], v[4:7], v[12:15]
	s_waitcnt lgkmcnt(1)
	v_cvt_pk_bf16_f32 v12, v48, v49
	v_cvt_pk_bf16_f32 v13, v50, v51
	s_waitcnt lgkmcnt(0)
	v_cvt_pk_bf16_f32 v14, v52, v53
	v_cvt_pk_bf16_f32 v15, v54, v55
	s_nop 0
	v_mfma_f32_16x16x32_bf16 v[0:3], v[12:15], v[0:3], v[8:11]
	s_waitcnt vmcnt(0)
	s_nop 1
	v_lshlrev_b32_e32 v8, 16, v61
	s_nop 3
	v_pk_add_f32 v[0:1], v[4:5], v[0:1]
	v_pk_add_f32 v[2:3], v[6:7], v[2:3]
	v_fma_f32 v0, v124, v56, v0
	v_mul_f32_e32 v4, 0x3d372713, v0
	v_mul_f32_e32 v4, v0, v4
	v_fma_f32 v4, v0, v4, v0
	v_mul_f32_e32 v4, 0x3f4c422a, v4
	v_mul_f32_e32 v4, 0x4038aa3b, v4
	v_exp_f32_e32 v4, v4
	v_fmac_f32_e32 v1, v124, v57
	v_mul_f32_e32 v5, 0x3d372713, v1
	v_mul_f32_e32 v5, v1, v5
	v_fma_f32 v5, v1, v5, v1
	v_add_f32_e32 v4, 1.0, v4
	v_mul_f32_e32 v5, 0x3f4c422a, v5
	v_rcp_f32_e32 v4, v4
	v_mul_f32_e32 v5, 0x4038aa3b, v5
	v_exp_f32_e32 v5, v5
	v_mul_f32_e32 v0, 0.5, v0
	v_fma_f32 v4, v4, -2.0, 2.0
	v_mul_f32_e32 v0, v0, v4
	v_add_f32_e32 v4, 1.0, v5
	v_rcp_f32_e32 v6, v4
	v_cvt_pk_bf16_f32 v0, v0, v81
	v_lshl_add_u64 v[4:5], v[92:93], 0, v[20:21]
	global_store_short v[4:5], v0, off
	v_mul_f32_e32 v0, 0.5, v1
	v_fma_f32 v1, v6, -2.0, 2.0
	v_mul_f32_e32 v0, v0, v1
	v_fma_f32 v2, v124, v58, v2
	v_cvt_pk_bf16_f32 v4, v0, v81
	v_mul_f32_e32 v0, 0x3d372713, v2
	v_mul_f32_e32 v0, v2, v0
	v_fma_f32 v0, v2, v0, v2
	v_mul_f32_e32 v0, 0x3f4c422a, v0
	v_mul_f32_e32 v0, 0x4038aa3b, v0
	v_exp_f32_e32 v5, v0
	v_lshl_add_u64 v[0:1], v[92:93], 0, v[18:19]
	v_fmac_f32_e32 v3, v124, v8
	global_store_short v[0:1], v4, off
	v_mul_f32_e32 v0, 0.5, v2
	v_mul_f32_e32 v2, 0x3d372713, v3
	v_mul_f32_e32 v2, v3, v2
	v_add_f32_e32 v1, 1.0, v5
	v_fma_f32 v2, v3, v2, v3
	v_rcp_f32_e32 v1, v1
	v_mul_f32_e32 v2, 0x3f4c422a, v2
	v_mul_f32_e32 v2, 0x4038aa3b, v2
	v_exp_f32_e32 v2, v2
	v_fma_f32 v1, v1, -2.0, 2.0
	v_mul_f32_e32 v0, v0, v1
	v_cvt_pk_bf16_f32 v4, v0, v81
	v_add_f32_e32 v0, 1.0, v2
	v_rcp_f32_e32 v2, v0
	v_lshl_add_u64 v[0:1], v[92:93], 0, v[16:17]
	global_store_short v[0:1], v4, off
	v_mul_f32_e32 v0, 0.5, v3
	v_fma_f32 v1, v2, -2.0, 2.0
	v_mul_f32_e32 v0, v0, v1
	v_cvt_pk_bf16_f32 v2, v0, v81
	v_lshl_add_u64 v[0:1], v[92:93], 0, v[22:23]
	global_store_short v[0:1], v2, off
	s_waitcnt lgkmcnt(0)
	s_cbranch_scc0 .LBB0_547
